# K QK-norm precomputed once in the idle part of the cumsum step (attention copies K tiles straight to LDS); mLSTM: step-3 row sums via DPP, C-update MFMA chain with 6-deep LDS operand prefetch
# baseline (speedup 1.0000x reference)
.LBB0_148:
	s_bitcmp1_b32 s4, 0
	s_cselect_b32 s11, 0x11800, 0
	s_add_i32 s14, s11, 0
	v_add_u32_e32 v90, s14, v199
	v_add3_u32 v91, s14, v96, v205
	v_add_u32_e32 v7, v90, v218
	v_add_u32_e32 v2, v90, v219
	v_add_u32_e32 v11, v90, v220
	v_add_u32_e32 v1, v90, v221
	s_waitcnt vmcnt(0)
	ds_write_b128 v91, v[106:109]
	ds_write_b128 v7, v[110:113] offset:36864
	ds_write_b128 v91, v[114:117] offset:9216
	ds_write_b128 v2, v[118:121] offset:36864
	ds_write_b128 v91, v[122:125] offset:18432
	ds_write_b128 v11, v[126:129] offset:36864
	ds_write_b128 v91, v[130:133] offset:27648
	ds_write_b128 v1, v[134:137] offset:36864
	s_and_saveexec_b64 s[12:13], s[42:43]
	v_add_u32_e32 v3, s14, v203
	v_add_u32_e32 v3, 0x11400, v3
	ds_write_b32 v3, v189
	s_or_b64 exec, exec, s[12:13]
	s_waitcnt lgkmcnt(0)
	s_barrier
	s_cmp_eq_u32 s2, s4
	s_cselect_b64 s[12:13], -1, 0
	s_mov_b32 s14, 0
	s_and_b64 vcc, exec, s[12:13]
	s_cbranch_vccnz .LBB0_154
	s_sub_i32 s16, s2, s4
	s_lshl_b32 s15, s16, 8
	s_add_i32 s36, s15, 0xffffff00
	v_lshl_add_u32 v1, s36, 1, v204
	v_lshl_add_u32 v2, s36, 11, v174
	s_lshl_b32 s16, s16, 19
	v_subrev_u32_e32 v2, s74, v2
	v_add_u32_e32 v3, v1, v192
	s_add_i32 s17, s16, 0xfffa0000
	v_subrev_u32_e32 v3, s74, v3
	buffer_load_dwordx4 v[106:109], v2, s[76:79], 0 offen sc1
	buffer_load_dwordx4 v[110:113], v3, s[76:79], 0 offen sc1
	v_add_u32_e32 v2, s17, v174
	v_subrev_u32_e32 v2, s74, v2
	v_add_u32_e32 v3, v1, v194
	s_add_i32 s17, s16, 0xfffc0000
	v_subrev_u32_e32 v3, s74, v3
	buffer_load_dwordx4 v[114:117], v2, s[76:79], 0 offen sc1
	buffer_load_dwordx4 v[118:121], v3, s[76:79], 0 offen sc1
	v_add_u32_e32 v2, s17, v174
	v_subrev_u32_e32 v2, s74, v2
	v_add_u32_e32 v3, v1, v196
	s_add_i32 s16, s16, 0xfffe0000
	v_subrev_u32_e32 v3, s74, v3
	buffer_load_dwordx4 v[122:125], v2, s[76:79], 0 offen sc1
	buffer_load_dwordx4 v[126:129], v3, s[76:79], 0 offen sc1
	v_add_u32_e32 v2, s16, v174
	v_subrev_u32_e32 v2, s74, v2
	v_add_u32_e32 v1, v1, v198
	v_subrev_u32_e32 v1, s74, v1
	buffer_load_dwordx4 v[130:133], v2, s[76:79], 0 offen sc1
	buffer_load_dwordx4 v[134:137], v1, s[76:79], 0 offen sc1
	s_and_saveexec_b64 s[44:45], s[42:43]
	s_cbranch_execz .LBB0_153
	v_lshl_add_u64 v[2:3], s[36:37], 2, v[206:207]
	global_load_dword v189, v[2:3], off sc1

.LBB0_230:
	s_or_b64 exec, exec, s[12:13]
	s_nop 3
	v_lshl_add_u32 v64, v74, 1, s15
	v_mul_lo_u32 v78, v70, s93
	v_cvt_pk_bf16_f32 v77, v76, s0
	v_add_u32_e32 v64, v64, v78
	ds_write_b16 v64, v77
	s_waitcnt lgkmcnt(0)
	s_nop 1
	v_add_f32_dpp v76, v76, v76 quad_perm:[1,0,3,2] row_mask:0xf bank_mask:0xf
	s_waitcnt lgkmcnt(0)
	s_nop 1
	v_add_f32_dpp v76, v76, v76 quad_perm:[2,3,0,1] row_mask:0xf bank_mask:0xf
	s_waitcnt lgkmcnt(0)
	s_nop 1
	v_add_f32_dpp v76, v76, v76 row_half_mirror row_mask:0xf bank_mask:0xf
	s_nop 1
	v_mov_b32_dpp v77, v76 row_ror:8 row_mask:0xf bank_mask:0xf
	s_and_saveexec_b64 s[12:13], s[42:43]
	s_cbranch_execz .LBB0_232
	s_waitcnt lgkmcnt(0)
	v_add_f32_e32 v76, v76, v77
	v_lshl_add_u32 v77, v70, 2, 0
	v_add_u32_e32 v77, 0x20e00, v77
	ds_add_f32 v77, v76

.LBB0_234:
	s_or_b64 exec, exec, s[12:13]
	v_cvt_pk_bf16_f32 v65, v77, s0
	ds_write_b16 v64, v65 offset:144
	s_waitcnt lgkmcnt(0)
	s_nop 1
	v_add_f32_dpp v65, v77, v77 quad_perm:[1,0,3,2] row_mask:0xf bank_mask:0xf
	s_waitcnt lgkmcnt(0)
	s_nop 1
	v_add_f32_dpp v65, v65, v65 quad_perm:[2,3,0,1] row_mask:0xf bank_mask:0xf
	s_waitcnt lgkmcnt(0)
	s_nop 1
	v_add_f32_dpp v65, v65, v65 row_half_mirror row_mask:0xf bank_mask:0xf
	s_nop 1
	v_mov_b32_dpp v77, v65 row_ror:8 row_mask:0xf bank_mask:0xf
	s_and_saveexec_b64 s[12:13], s[42:43]
	s_cbranch_execz .LBB0_236
	s_waitcnt lgkmcnt(0)
	v_add_f32_e32 v65, v65, v77
	v_add_u32_e32 v76, 0x20e00, v76
	ds_add_f32 v76, v65

.LBB0_238:
	s_or_b64 exec, exec, s[12:13]
	v_cvt_pk_bf16_f32 v66, v76, s0
	ds_write_b16 v64, v66 offset:288
	s_waitcnt lgkmcnt(0)
	s_nop 1
	v_add_f32_dpp v66, v76, v76 quad_perm:[1,0,3,2] row_mask:0xf bank_mask:0xf
	s_waitcnt lgkmcnt(0)
	s_nop 1
	v_add_f32_dpp v66, v66, v66 quad_perm:[2,3,0,1] row_mask:0xf bank_mask:0xf
	s_waitcnt lgkmcnt(0)
	s_nop 1
	v_add_f32_dpp v66, v66, v66 row_half_mirror row_mask:0xf bank_mask:0xf
	s_nop 1
	v_mov_b32_dpp v76, v66 row_ror:8 row_mask:0xf bank_mask:0xf
	s_and_saveexec_b64 s[12:13], s[42:43]
	s_cbranch_execz .LBB0_240
	s_waitcnt lgkmcnt(0)
	v_add_f32_e32 v66, v66, v76
	v_add_u32_e32 v65, 0x20e00, v65
	ds_add_f32 v65, v66

.LBB0_242:
	s_or_b64 exec, exec, s[12:13]
	v_cvt_pk_bf16_f32 v67, v66, s0
	ds_write_b16 v64, v67 offset:432
	s_waitcnt lgkmcnt(0)
	s_nop 1
	v_add_f32_dpp v64, v66, v66 quad_perm:[1,0,3,2] row_mask:0xf bank_mask:0xf
	s_waitcnt lgkmcnt(0)
	s_nop 1
	v_add_f32_dpp v64, v64, v64 quad_perm:[2,3,0,1] row_mask:0xf bank_mask:0xf
	s_waitcnt lgkmcnt(0)
	s_nop 1
	v_add_f32_dpp v64, v64, v64 row_half_mirror row_mask:0xf bank_mask:0xf
	s_nop 1
	v_mov_b32_dpp v66, v64 row_ror:8 row_mask:0xf bank_mask:0xf
	s_and_saveexec_b64 s[12:13], s[42:43]
	s_cbranch_execz .LBB0_244
	s_waitcnt lgkmcnt(0)
	v_add_f32_e32 v64, v64, v66
	v_add_u32_e32 v65, 0x20e00, v65
	ds_add_f32 v65, v64

.LBB0_249:
	s_or_b64 exec, exec, s[12:13]
	s_nop 3
	v_lshl_add_u32 v64, v73, 1, s15
	v_add_u32_e32 v64, v64, v74
	v_cvt_pk_bf16_f32 v76, v75, s0
	ds_write_b16 v64, v76
	s_waitcnt lgkmcnt(1)
	s_nop 1
	v_add_f32_dpp v74, v75, v75 quad_perm:[1,0,3,2] row_mask:0xf bank_mask:0xf
	s_waitcnt lgkmcnt(0)
	s_nop 1
	v_add_f32_dpp v74, v74, v74 quad_perm:[2,3,0,1] row_mask:0xf bank_mask:0xf
	s_waitcnt lgkmcnt(0)
	s_nop 1
	v_add_f32_dpp v74, v74, v74 row_half_mirror row_mask:0xf bank_mask:0xf
	s_nop 1
	v_mov_b32_dpp v75, v74 row_ror:8 row_mask:0xf bank_mask:0xf
	s_and_saveexec_b64 s[12:13], s[42:43]
	s_cbranch_execz .LBB0_251
	s_waitcnt lgkmcnt(0)
	v_add_f32_e32 v74, v74, v75
	v_add_u32_e32 v72, 0x20e00, v72
	ds_add_f32 v72, v74

.LBB0_253:
	s_or_b64 exec, exec, s[12:13]
	v_cvt_pk_bf16_f32 v65, v74, s0
	ds_write_b16 v64, v65 offset:144
	s_waitcnt lgkmcnt(0)
	s_nop 1
	v_add_f32_dpp v65, v74, v74 quad_perm:[1,0,3,2] row_mask:0xf bank_mask:0xf
	s_waitcnt lgkmcnt(0)
	s_nop 1
	v_add_f32_dpp v65, v65, v65 quad_perm:[2,3,0,1] row_mask:0xf bank_mask:0xf
	s_waitcnt lgkmcnt(0)
	s_nop 1
	v_add_f32_dpp v65, v65, v65 row_half_mirror row_mask:0xf bank_mask:0xf
	s_nop 1
	v_mov_b32_dpp v74, v65 row_ror:8 row_mask:0xf bank_mask:0xf
	s_and_saveexec_b64 s[12:13], s[42:43]
	s_cbranch_execz .LBB0_255
	s_waitcnt lgkmcnt(0)
	v_add_f32_e32 v65, v65, v74
	v_add_u32_e32 v72, 0x20e00, v72
	ds_add_f32 v72, v65

.LBB0_257:
	s_or_b64 exec, exec, s[12:13]
	v_cvt_pk_bf16_f32 v66, v72, s0
	ds_write_b16 v64, v66 offset:288
	s_waitcnt lgkmcnt(0)
	s_nop 1
	v_add_f32_dpp v66, v72, v72 quad_perm:[1,0,3,2] row_mask:0xf bank_mask:0xf
	s_waitcnt lgkmcnt(0)
	s_nop 1
	v_add_f32_dpp v66, v66, v66 quad_perm:[2,3,0,1] row_mask:0xf bank_mask:0xf
	s_waitcnt lgkmcnt(0)
	s_nop 1
	v_add_f32_dpp v66, v66, v66 row_half_mirror row_mask:0xf bank_mask:0xf
	s_nop 1
	v_mov_b32_dpp v72, v66 row_ror:8 row_mask:0xf bank_mask:0xf
	s_and_saveexec_b64 s[12:13], s[42:43]
	s_cbranch_execz .LBB0_259
	s_waitcnt lgkmcnt(0)
	v_add_f32_e32 v66, v66, v72
	v_add_u32_e32 v65, 0x20e00, v65
	ds_add_f32 v65, v66

.LBB0_264:
	v_mul_lo_u32 v64, v68, s1
	v_lshlrev_b32_e32 v65, 5, v69
	v_add3_u32 v70, 0, v64, v65
	s_waitcnt lgkmcnt(0)
	ds_read_b128 v[64:67], v70
	v_lshl_add_u32 v71, v69, 6, 0
	v_add_u32_e32 v86, 0x21000, v71
	ds_read_b128 v[70:73], v70 offset:16
	ds_read_b128 v[74:77], v86
	ds_read_b128 v[78:81], v86 offset:16
	ds_read_b128 v[82:85], v86 offset:32
	ds_read_b128 v[86:89], v86 offset:48
	s_waitcnt lgkmcnt(5)
	v_lshlrev_b32_e32 v90, 16, v64
	v_and_b32_e32 v64, 0xffff0000, v64
	s_waitcnt lgkmcnt(3)
	v_mul_f32_e32 v64, v75, v64
	v_fmac_f32_e32 v64, v74, v90
	v_lshlrev_b32_e32 v74, 16, v70
	v_and_b32_e32 v70, 0xffff0000, v70
	s_waitcnt lgkmcnt(1)
	v_mul_f32_e32 v70, v83, v70
	v_add_f32_e32 v64, 0, v64
	v_fmac_f32_e32 v70, v82, v74
	v_add_f32_e32 v64, v64, v70
	v_lshlrev_b32_e32 v70, 16, v65
	v_and_b32_e32 v65, 0xffff0000, v65
	v_mul_f32_e32 v65, v77, v65
	v_fmac_f32_e32 v65, v76, v70
	v_and_b32_e32 v70, 0xffff0000, v71
	v_add_f32_e32 v64, v64, v65
	v_lshlrev_b32_e32 v65, 16, v71
	v_mul_f32_e32 v70, v85, v70
	v_fmac_f32_e32 v70, v84, v65
	v_lshlrev_b32_e32 v65, 16, v66
	v_and_b32_e32 v66, 0xffff0000, v66
	v_mul_f32_e32 v66, v79, v66
	v_add_f32_e32 v64, v64, v70
	v_fmac_f32_e32 v66, v78, v65
	v_add_f32_e32 v64, v64, v66
	v_and_b32_e32 v66, 0xffff0000, v72
	v_lshlrev_b32_e32 v65, 16, v72
	s_waitcnt lgkmcnt(0)
	v_mul_f32_e32 v66, v87, v66
	v_fmac_f32_e32 v66, v86, v65
	v_add_f32_e32 v64, v64, v66
	v_and_b32_e32 v66, 0xffff0000, v67
	v_lshlrev_b32_e32 v65, 16, v67
	v_mul_f32_e32 v66, v81, v66
	v_fmac_f32_e32 v66, v80, v65
	v_add_f32_e32 v64, v64, v66
	v_and_b32_e32 v66, 0xffff0000, v73
	v_lshlrev_b32_e32 v65, 16, v73
	v_mul_f32_e32 v66, v89, v66
	v_fmac_f32_e32 v66, v88, v65
	v_add_f32_e32 v64, v64, v66
	v_cmp_eq_u32_e32 vcc, 0, v69
	s_waitcnt lgkmcnt(0)
	s_nop 1
	v_add_f32_dpp v64, v64, v64 quad_perm:[1,0,3,2] row_mask:0xf bank_mask:0xf
	s_waitcnt lgkmcnt(0)
	s_nop 1
	v_add_f32_dpp v64, v64, v64 quad_perm:[2,3,0,1] row_mask:0xf bank_mask:0xf
	s_nop 1
	v_mov_b32_dpp v65, v64 row_half_mirror row_mask:0xf bank_mask:0xf
	s_and_saveexec_b64 s[12:13], vcc
	s_cbranch_execz .LBB0_266
	s_waitcnt lgkmcnt(0)
	v_add_f32_e32 v64, v64, v65
	v_lshl_add_u32 v65, v68, 2, 0
	v_add_u32_e32 v65, 0x20d00, v65
	ds_write_b32 v65, v64
.LBB0_266:
	s_or_b64 exec, exec, s[12:13]
	s_add_u32 s12, s74, s4
	s_addc_u32 s13, s75, s31
	s_waitcnt lgkmcnt(0)
	v_lshl_add_u64 v[64:65], s[12:13], 0, v[96:97]
	v_add_co_u32_e32 v66, vcc, 0xf000000, v64
	s_waitcnt lgkmcnt(0)
	s_barrier
	v_lshrrev_b32_e32 v218, 5, v168
	s_nop 0
	v_addc_co_u32_e32 v67, vcc, 0, v65, vcc
	global_load_dwordx2 v[206:207], v[66:67], off sc1
	global_load_dwordx2 v[204:205], v[66:67], off offset:2048 sc1
	v_add_co_u32_e32 v66, vcc, 0xf001000, v64
	v_lshlrev_b32_e32 v217, 4, v218
	s_nop 0
	v_addc_co_u32_e32 v67, vcc, 0, v65, vcc
	global_load_dwordx2 v[202:203], v[66:67], off sc1
	global_load_dwordx2 v[200:201], v[66:67], off offset:2048 sc1
	v_add_co_u32_e32 v66, vcc, 0xf002000, v64
	v_add_u32_e32 v208, 0, v217
	s_nop 0
	v_addc_co_u32_e32 v67, vcc, 0, v65, vcc
	v_add_co_u32_e32 v64, vcc, 0xf003000, v64
	global_load_dwordx2 v[198:199], v[66:67], off sc1
	global_load_dwordx2 v[196:197], v[66:67], off offset:2048 sc1
	v_addc_co_u32_e32 v65, vcc, 0, v65, vcc
	global_load_dwordx2 v[194:195], v[64:65], off sc1
	global_load_dwordx2 v[192:193], v[64:65], off offset:2048 sc1
	v_lshlrev_b32_e32 v64, 4, v168
	global_load_dwordx4 v[152:155], v64, s[50:51]
	v_mov_b32_e32 v64, s10
	ds_read_b32 v96, v64
	v_or_b32_e32 v64, s11, v215
	v_lshlrev_b32_e32 v68, 3, v218
	v_mul_u32_u24_e32 v69, 0x110, v215
	v_mad_u64_u32 v[64:65], s[12:13], v64, s93, v[208:209]
	v_add3_u32 v176, 0, v68, v69
	ds_read_b128 v[168:171], v64 offset:53248
	ds_read_b128 v[164:167], v64 offset:53280
	ds_read_b128 v[160:163], v64 offset:53312
	ds_read_b128 v[156:159], v64 offset:53344
	ds_read2_b64 v[68:71], v176 offset1:2
	ds_read2_b64 v[172:175], v176 offset0:4 offset1:6
	v_cvt_pk_bf16_f32 v64, v0, v1
	v_cvt_pk_bf16_f32 v65, v2, v3
	v_cvt_pk_bf16_f32 v66, v4, v5
	v_cvt_pk_bf16_f32 v67, v6, v7
	v_add_u32_e32 v177, 0x2000, v176
	v_cvt_pk_bf16_f32 v232, v8, v9
	s_waitcnt lgkmcnt(1)
	v_mfma_f32_32x32x16_bf16 v[80:95], v[68:71], v[64:67], 0
	ds_read2_b64 v[68:71], v177 offset0:64 offset1:66
	v_cvt_pk_bf16_f32 v233, v10, v11
	v_cvt_pk_bf16_f32 v234, v12, v13
	v_cvt_pk_bf16_f32 v235, v14, v15
	s_add_i32 s12, 0, 0x20b00
	v_add_u32_e32 v220, s12, v217
	v_add_u32_e32 v219, s15, v217
	s_waitcnt lgkmcnt(1)
	v_mfma_f32_32x32x16_bf16 v[80:95], v[172:175], v[232:235], v[80:95]
	ds_read2_b64 v[172:175], v177 offset0:68 offset1:70
	s_add_i32 s13, 0, 0x20d00
	s_add_i32 s15, 0, 0x20e00
	s_add_i32 s42, 0, 0x20f00
	s_movk_i32 s43, 0x840
	v_or_b32_e32 v216, 32, v215
	v_pk_mul_f32 v[14:15], v[14:15], v[96:97] op_sel_hi:[1,0]
	s_waitcnt lgkmcnt(1)
	v_mfma_f32_32x32x16_bf16 v[64:79], v[68:71], v[64:67], 0
	v_mul_f32_e64 v12, v12, v96
	v_mul_f32_e64 v13, v13, v96
	v_mul_f32_e64 v10, v10, v96
	v_mul_f32_e64 v11, v11, v96
	v_mul_f32_e64 v8, v8, v96
	v_mul_f32_e64 v9, v9, v96
	v_pk_mul_f32 v[6:7], v[6:7], v[96:97] op_sel_hi:[1,0]
	v_pk_mul_f32 v[4:5], v[4:5], v[96:97] op_sel_hi:[1,0]
	v_pk_mul_f32 v[2:3], v[2:3], v[96:97] op_sel_hi:[1,0]
	v_pk_mul_f32 v[0:1], v[0:1], v[96:97] op_sel_hi:[1,0]
	s_waitcnt lgkmcnt(0)
	v_mfma_f32_32x32x16_bf16 v[64:79], v[172:175], v[232:235], v[64:79]
	ds_read2_b64 v[232:235], v176 offset0:8 offset1:10
	v_cvt_pk_bf16_f32 v172, v16, v17
	v_cvt_pk_bf16_f32 v173, v18, v19
	v_cvt_pk_bf16_f32 v174, v20, v21
	v_cvt_pk_bf16_f32 v175, v22, v23
	v_pk_mul_f32 v[22:23], v[22:23], v[96:97] op_sel_hi:[1,0]
	v_pk_mul_f32 v[20:21], v[20:21], v[96:97] op_sel_hi:[1,0]
	s_waitcnt lgkmcnt(0)
	v_mfma_f32_32x32x16_bf16 v[80:95], v[232:235], v[172:175], v[80:95]
	ds_read2_b64 v[232:235], v177 offset0:72 offset1:74
	v_mul_f32_e64 v18, v18, v96
	v_mul_f32_e64 v19, v19, v96
	v_mul_f32_e64 v16, v16, v96
	v_mul_f32_e64 v17, v17, v96
	s_waitcnt lgkmcnt(0)
	v_mfma_f32_32x32x16_bf16 v[64:79], v[232:235], v[172:175], v[64:79]
	ds_read2_b64 v[232:235], v176 offset0:12 offset1:14
	v_cvt_pk_bf16_f32 v172, v24, v25
	v_cvt_pk_bf16_f32 v173, v26, v27
	v_cvt_pk_bf16_f32 v174, v28, v29
	v_cvt_pk_bf16_f32 v175, v30, v31
	v_pk_mul_f32 v[30:31], v[30:31], v[96:97] op_sel_hi:[1,0]
	v_pk_mul_f32 v[28:29], v[28:29], v[96:97] op_sel_hi:[1,0]
	s_waitcnt lgkmcnt(0)
	v_mfma_f32_32x32x16_bf16 v[80:95], v[232:235], v[172:175], v[80:95]
	ds_read2_b64 v[232:235], v177 offset0:76 offset1:78
	v_mul_f32_e64 v26, v26, v96
	v_mul_f32_e64 v27, v27, v96
	v_mul_f32_e64 v24, v24, v96
	v_mul_f32_e64 v25, v25, v96
	s_waitcnt lgkmcnt(0)
	v_mfma_f32_32x32x16_bf16 v[64:79], v[232:235], v[172:175], v[64:79]
	ds_read2_b64 v[232:235], v176 offset0:16 offset1:18
	v_cvt_pk_bf16_f32 v172, v32, v33
	v_cvt_pk_bf16_f32 v173, v34, v35
	v_cvt_pk_bf16_f32 v174, v36, v37
	v_cvt_pk_bf16_f32 v175, v38, v39
	v_pk_mul_f32 v[38:39], v[38:39], v[96:97] op_sel_hi:[1,0]
	v_pk_mul_f32 v[36:37], v[36:37], v[96:97] op_sel_hi:[1,0]
	s_waitcnt lgkmcnt(0)
	v_mfma_f32_32x32x16_bf16 v[80:95], v[232:235], v[172:175], v[80:95]
	ds_read2_b64 v[232:235], v177 offset0:80 offset1:82
	v_mul_f32_e64 v34, v34, v96
	v_mul_f32_e64 v35, v35, v96
	v_mul_f32_e64 v32, v32, v96
	v_mul_f32_e64 v33, v33, v96
	s_waitcnt lgkmcnt(0)
	v_mfma_f32_32x32x16_bf16 v[64:79], v[232:235], v[172:175], v[64:79]
	ds_read2_b64 v[232:235], v176 offset0:20 offset1:22
	v_cvt_pk_bf16_f32 v172, v40, v41
	v_cvt_pk_bf16_f32 v173, v42, v43
	v_cvt_pk_bf16_f32 v174, v44, v45
	v_cvt_pk_bf16_f32 v175, v46, v47
	v_pk_mul_f32 v[46:47], v[46:47], v[96:97] op_sel_hi:[1,0]
	v_pk_mul_f32 v[44:45], v[44:45], v[96:97] op_sel_hi:[1,0]
	s_waitcnt lgkmcnt(0)
	v_mfma_f32_32x32x16_bf16 v[80:95], v[232:235], v[172:175], v[80:95]
	ds_read2_b64 v[232:235], v177 offset0:84 offset1:86
	v_mul_f32_e64 v42, v42, v96
	v_mul_f32_e64 v43, v43, v96
	v_mul_f32_e64 v40, v40, v96
	v_mul_f32_e64 v41, v41, v96
	s_waitcnt lgkmcnt(0)
	v_mfma_f32_32x32x16_bf16 v[64:79], v[232:235], v[172:175], v[64:79]
	ds_read2_b64 v[232:235], v176 offset0:24 offset1:26
	v_cvt_pk_bf16_f32 v172, v48, v49
	v_cvt_pk_bf16_f32 v173, v50, v51
	v_cvt_pk_bf16_f32 v174, v52, v53
	v_cvt_pk_bf16_f32 v175, v54, v55
	v_pk_mul_f32 v[54:55], v[54:55], v[96:97] op_sel_hi:[1,0]
	v_pk_mul_f32 v[52:53], v[52:53], v[96:97] op_sel_hi:[1,0]
	s_waitcnt lgkmcnt(0)
	v_mfma_f32_32x32x16_bf16 v[80:95], v[232:235], v[172:175], v[80:95]
	ds_read2_b64 v[232:235], v177 offset0:88 offset1:90
	v_mul_f32_e64 v50, v50, v96
	v_mul_f32_e64 v51, v51, v96
	v_mul_f32_e64 v48, v48, v96
	v_mul_f32_e64 v49, v49, v96
	s_waitcnt lgkmcnt(0)
	v_mfma_f32_32x32x16_bf16 v[64:79], v[232:235], v[172:175], v[64:79]
	ds_read2_b64 v[232:235], v176 offset0:28 offset1:30
	v_cvt_pk_bf16_f32 v172, v56, v57
	v_cvt_pk_bf16_f32 v173, v58, v59
	v_cvt_pk_bf16_f32 v174, v60, v61
	v_cvt_pk_bf16_f32 v175, v62, v63
	v_lshl_add_u32 v176, v215, 1, s2
	v_pk_mul_f32 v[62:63], v[62:63], v[96:97] op_sel_hi:[1,0]
	s_waitcnt lgkmcnt(0)
	v_mfma_f32_32x32x16_bf16 v[80:95], v[232:235], v[172:175], v[80:95]
	ds_read2_b64 v[232:235], v177 offset0:92 offset1:94
	v_mad_u32_u24 v177, v215, s93, v219
	v_mul_f32_e64 v60, v60, v96
	v_mul_f32_e64 v61, v61, v96
	v_mul_f32_e64 v58, v58, v96
	v_mul_f32_e64 v59, v59, v96
	v_pk_mul_f32 v[56:57], v[56:57], v[96:97] op_sel_hi:[1,0]
	s_waitcnt lgkmcnt(0)
	v_mfma_f32_32x32x16_bf16 v[64:79], v[232:235], v[172:175], v[64:79]
	ds_read_b128 v[172:175], v220
	ds_read_b128 v[232:235], v220 offset:32
	ds_read_b128 v[236:239], v220 offset:64
	ds_read_b128 v[240:243], v220 offset:96
	s_waitcnt lgkmcnt(3)
	v_pk_mul_f32 v[82:83], v[82:83], v[174:175]
	s_waitcnt lgkmcnt(2)
	v_pk_mul_f32 v[86:87], v[86:87], v[234:235]
	s_waitcnt lgkmcnt(1)
	v_pk_mul_f32 v[90:91], v[90:91], v[238:239]
	v_pk_mul_f32 v[88:89], v[88:89], v[236:237]
	v_pk_mul_f32 v[84:85], v[84:85], v[232:233]
	ds_read_b128 v[232:235], v177
	ds_read_b128 v[236:239], v177 offset:32
	s_waitcnt lgkmcnt(2)
	v_pk_mul_f32 v[94:95], v[94:95], v[242:243]
	v_pk_mul_f32 v[92:93], v[92:93], v[240:241]
	v_pk_mul_f32 v[80:81], v[80:81], v[172:173]
	s_waitcnt lgkmcnt(1)
	s_nop 0
	v_mfma_f32_32x32x16_bf16 v[80:95], v[232:235], v[168:171], v[80:95]
	ds_read_b128 v[232:235], v177 offset:64
	s_waitcnt lgkmcnt(1)
	v_mfma_f32_32x32x16_bf16 v[80:95], v[236:239], v[164:167], v[80:95]
	s_waitcnt lgkmcnt(0)
	v_mfma_f32_32x32x16_bf16 v[80:95], v[232:235], v[160:163], v[80:95]
	ds_read_b128 v[232:235], v177 offset:96
	v_add_u32_e32 v177, s13, v217
	s_waitcnt lgkmcnt(0)
	v_mfma_f32_32x32x16_bf16 v[80:95], v[232:235], v[156:159], v[80:95]
	ds_read_b128 v[232:235], v177
	v_add_u32_e32 v177, s15, v217
	ds_read_b128 v[236:239], v177
	v_add_u32_e32 v177, s42, v217
	ds_read_b128 v[240:243], v177
	s_waitcnt lgkmcnt(1)
	v_fma_f32 v172, v172, v232, v236
	v_fmac_f32_e32 v239, v175, v235
	s_waitcnt lgkmcnt(0)
	v_max_f32_e32 v177, v240, v240
	v_max_f32_e64 v172, |v172|, v177
	v_rcp_f32_e32 v172, v172
	s_nop 0
	v_mul_f32_e32 v80, v80, v172
	v_cvt_pk_bf16_f32 v172, v80, s0
	v_mad_u32_u24 v80, v218, s43, v176
	ds_write_b16 v80, v172
	v_fma_f32 v172, v173, v233, v237
	v_max_f32_e32 v173, v241, v241
	v_max_f32_e64 v172, |v172|, v173
	v_rcp_f32_e32 v172, v172
	s_nop 0
	v_mul_f32_e32 v81, v81, v172
	v_cvt_pk_bf16_f32 v81, v81, s0
	ds_write_b16 v80, v81 offset:528
	v_fma_f32 v81, v174, v234, v238
	v_max_f32_e32 v172, v242, v242
	v_max_f32_e64 v81, |v81|, v172
	v_rcp_f32_e32 v81, v81
	s_nop 0
	v_mul_f32_e32 v81, v82, v81
	v_cvt_pk_bf16_f32 v81, v81, s0
	ds_write_b16 v80, v81 offset:1056
	v_max_f32_e32 v81, v243, v243
	v_max_f32_e64 v81, |v239|, v81
	v_rcp_f32_e32 v81, v81
	s_nop 0
	v_mul_f32_e32 v81, v83, v81
	v_cvt_pk_bf16_f32 v81, v81, s0
	ds_write_b16 v80, v81 offset:1584
	v_lshl_or_b32 v81, v218, 2, 8
	v_lshlrev_b32_e32 v82, 2, v81
	v_add_u32_e32 v83, s12, v82
	ds_read_b128 v[172:175], v83
	v_add_u32_e32 v83, s13, v82
	ds_read_b128 v[232:235], v83
	v_add_u32_e32 v83, s15, v82
	v_add_u32_e32 v82, s42, v82
	ds_read_b128 v[236:239], v83
	ds_read_b128 v[240:243], v82
	v_mad_u32_u24 v81, v81, s85, v176
	s_waitcnt lgkmcnt(1)
	v_fma_f32 v82, v172, v232, v236
	s_waitcnt lgkmcnt(0)
	v_max_f32_e32 v83, v240, v240
	v_max_f32_e64 v82, |v82|, v83
	v_rcp_f32_e32 v82, v82
	v_max_f32_e32 v83, v241, v241
	v_fmac_f32_e32 v239, v175, v235
	v_mul_f32_e32 v82, v84, v82
	v_cvt_pk_bf16_f32 v82, v82, s0
	ds_write_b16 v81, v82
	v_fma_f32 v82, v173, v233, v237
	v_max_f32_e64 v82, |v82|, v83
	v_rcp_f32_e32 v82, v82
	v_max_f32_e32 v83, v242, v242
	v_mul_f32_e32 v82, v85, v82
	v_cvt_pk_bf16_f32 v82, v82, s0
	ds_write_b16 v80, v82 offset:4752
	v_fma_f32 v82, v174, v234, v238
	v_max_f32_e64 v82, |v82|, v83
	v_rcp_f32_e32 v82, v82
	s_nop 0
	v_mul_f32_e32 v82, v86, v82
	v_cvt_pk_bf16_f32 v82, v82, s0
	ds_write_b16 v80, v82 offset:5280
	v_max_f32_e32 v82, v243, v243
	v_max_f32_e64 v82, |v239|, v82
	v_rcp_f32_e32 v82, v82
	v_or_b32_e32 v86, 64, v217
	v_mul_f32_e32 v82, v87, v82
	v_cvt_pk_bf16_f32 v82, v82, s0
	ds_write_b16 v80, v82 offset:5808
	v_add_u32_e32 v87, s13, v86
	v_add_u32_e32 v82, s12, v86
	ds_read_b128 v[172:175], v87
	v_add_u32_e32 v87, s15, v86
	v_add_u32_e32 v86, s42, v86
	ds_read_b128 v[82:85], v82
	ds_read_b128 v[236:239], v86
	ds_read_b128 v[232:235], v87
	s_waitcnt lgkmcnt(1)
	v_max_f32_e32 v86, v236, v236
	s_waitcnt lgkmcnt(0)
	v_fma_f32 v82, v82, v172, v232
	v_max_f32_e64 v82, |v82|, v86
	v_rcp_f32_e32 v82, v82
	v_fmac_f32_e32 v235, v85, v175
	v_mul_f32_e32 v82, v88, v82
	v_cvt_pk_bf16_f32 v82, v82, s0
	ds_write_b16 v81, v82 offset:4224
	v_fma_f32 v82, v83, v173, v233
	v_max_f32_e32 v83, v237, v237
	v_max_f32_e64 v82, |v82|, v83
	v_rcp_f32_e32 v82, v82
	v_max_f32_e32 v83, v238, v238
	v_mul_f32_e32 v82, v89, v82
	v_cvt_pk_bf16_f32 v82, v82, s0
	ds_write_b16 v80, v82 offset:8976
	v_fma_f32 v82, v84, v174, v234
	v_max_f32_e64 v82, |v82|, v83
	v_rcp_f32_e32 v82, v82
	s_nop 0
	v_mul_f32_e32 v82, v90, v82
	v_cvt_pk_bf16_f32 v82, v82, s0
	ds_write_b16 v80, v82 offset:9504
	v_max_f32_e32 v82, v239, v239
	v_max_f32_e64 v82, |v235|, v82
	v_rcp_f32_e32 v82, v82
	v_or_b32_e32 v90, 0x60, v217
	v_add_u32_e32 v86, s13, v90
	v_mul_f32_e32 v82, v91, v82
	v_cvt_pk_bf16_f32 v82, v82, s0
	ds_write_b16 v80, v82 offset:10032
	v_add_u32_e32 v82, s12, v90
	v_add_u32_e32 v91, s15, v90
	v_add_u32_e32 v90, s42, v90
	ds_read_b128 v[82:85], v82
	ds_read_b128 v[86:89], v86
	ds_read_b128 v[172:175], v91
	ds_read_b128 v[232:235], v90
	s_waitcnt lgkmcnt(1)
	v_fma_f32 v82, v82, v86, v172
	s_waitcnt lgkmcnt(0)
	v_max_f32_e32 v86, v232, v232
	v_max_f32_e64 v82, |v82|, v86
	v_rcp_f32_e32 v82, v82
	v_fmac_f32_e32 v175, v85, v89
	v_mul_f32_e32 v82, v92, v82
	v_cvt_pk_bf16_f32 v82, v82, s0
	ds_write_b16 v81, v82 offset:8448
	v_fma_f32 v82, v83, v87, v173
	v_max_f32_e32 v83, v233, v233
	v_max_f32_e64 v82, |v82|, v83
	v_rcp_f32_e32 v82, v82
	v_max_f32_e32 v83, v234, v234
	v_mul_f32_e32 v82, v93, v82
	v_cvt_pk_bf16_f32 v82, v82, s0
	ds_write_b16 v80, v82 offset:13200
	v_fma_f32 v82, v84, v88, v174
	v_max_f32_e64 v82, |v82|, v83
	v_rcp_f32_e32 v82, v82
	s_nop 0
	v_mul_f32_e32 v82, v94, v82
	v_cvt_pk_bf16_f32 v82, v82, s0
	ds_write_b16 v80, v82 offset:13728
	v_max_f32_e32 v82, v235, v235
	v_max_f32_e64 v82, |v175|, v82
	v_rcp_f32_e32 v82, v82
	v_mad_u32_u24 v94, v216, s93, v219
	v_mul_f32_e32 v82, v95, v82
	v_cvt_pk_bf16_f32 v82, v82, s0
	ds_write_b16 v80, v82 offset:14256
	ds_read_b128 v[82:85], v220 offset:128
	ds_read_b128 v[86:89], v220 offset:160
	ds_read_b128 v[90:93], v220 offset:192
	ds_read_b128 v[172:175], v220 offset:224
	s_waitcnt lgkmcnt(3)
	v_pk_mul_f32 v[66:67], v[66:67], v[84:85]
	s_waitcnt lgkmcnt(2)
	v_pk_mul_f32 v[68:69], v[68:69], v[86:87]
	s_waitcnt lgkmcnt(1)
	v_pk_mul_f32 v[72:73], v[72:73], v[90:91]
	v_pk_mul_f32 v[74:75], v[74:75], v[92:93]
	v_pk_mul_f32 v[70:71], v[70:71], v[88:89]
	ds_read_b128 v[86:89], v94
	ds_read_b128 v[90:93], v94 offset:32
	s_waitcnt lgkmcnt(2)
	v_pk_mul_f32 v[76:77], v[76:77], v[172:173]
	v_pk_mul_f32 v[78:79], v[78:79], v[174:175]
	v_pk_mul_f32 v[64:65], v[64:65], v[82:83]
	s_waitcnt lgkmcnt(1)
	s_nop 0
	v_mfma_f32_32x32x16_bf16 v[64:79], v[86:89], v[168:171], v[64:79]
	ds_read_b128 v[86:89], v94 offset:64
	s_waitcnt lgkmcnt(1)
	v_mfma_f32_32x32x16_bf16 v[64:79], v[90:93], v[164:167], v[64:79]
	s_waitcnt lgkmcnt(0)
	v_mfma_f32_32x32x16_bf16 v[64:79], v[86:89], v[160:163], v[64:79]
	ds_read_b128 v[86:89], v94 offset:96
	v_or_b32_e32 v94, 0x80, v217
	v_add_u32_e32 v90, s15, v94
	ds_read_b128 v[90:93], v90
	s_waitcnt lgkmcnt(1)
	v_mfma_f32_32x32x16_bf16 v[64:79], v[86:89], v[156:159], v[64:79]
	v_add_u32_e32 v86, s13, v94
	v_add_u32_e32 v94, s42, v94
	ds_read_b128 v[86:89], v86
	ds_read_b128 v[172:175], v94
	s_waitcnt lgkmcnt(1)
	v_fma_f32 v82, v82, v86, v90
	s_waitcnt lgkmcnt(0)
	v_max_f32_e32 v86, v172, v172
	v_max_f32_e64 v82, |v82|, v86
	v_rcp_f32_e32 v82, v82
	v_fmac_f32_e32 v93, v85, v89
	v_or_b32_e32 v90, 0xa0, v217
	v_add_u32_e32 v86, s15, v90
	v_mul_f32_e32 v64, v64, v82
	v_cvt_pk_bf16_f32 v64, v64, s0
	ds_write_b16 v81, v64 offset:12672
	v_fma_f32 v64, v83, v87, v91
	v_max_f32_e32 v82, v173, v173
	v_max_f32_e64 v64, |v64|, v82
	v_rcp_f32_e32 v64, v64
	v_add_u32_e32 v82, s13, v90
	v_mul_f32_e32 v64, v65, v64
	v_cvt_pk_bf16_f32 v64, v64, s0
	ds_write_b16 v80, v64 offset:17424
	v_fma_f32 v64, v84, v88, v92
	v_max_f32_e32 v65, v174, v174
	v_max_f32_e64 v64, |v64|, v65
	v_rcp_f32_e32 v64, v64
	s_nop 0
	v_mul_f32_e32 v64, v66, v64
	v_cvt_pk_bf16_f32 v64, v64, s0
	ds_write_b16 v80, v64 offset:17952
	v_max_f32_e32 v64, v175, v175
	v_max_f32_e64 v64, |v93|, v64
	v_rcp_f32_e32 v64, v64
	s_nop 0
	v_mul_f32_e32 v64, v67, v64
	v_cvt_pk_bf16_f32 v64, v64, s0
	ds_write_b16 v80, v64 offset:18480
	v_add_u32_e32 v64, s12, v90
	v_add_u32_e32 v90, s42, v90
	ds_read_b128 v[64:67], v64
	ds_read_b128 v[82:85], v82
	ds_read_b128 v[86:89], v86
	ds_read_b128 v[90:93], v90
	s_waitcnt lgkmcnt(1)
	v_fma_f32 v64, v64, v82, v86
	s_waitcnt lgkmcnt(0)
	v_max_f32_e32 v82, v90, v90
	v_max_f32_e64 v64, |v64|, v82
	v_rcp_f32_e32 v64, v64
	v_fmac_f32_e32 v89, v67, v85
	v_or_b32_e32 v86, 0xc0, v217
	v_add_u32_e32 v82, s15, v86
	v_mul_f32_e32 v64, v68, v64
	v_cvt_pk_bf16_f32 v64, v64, s0
	ds_write_b16 v81, v64 offset:16896
	v_fma_f32 v64, v65, v83, v87
	v_max_f32_e32 v65, v91, v91
	v_max_f32_e64 v64, |v64|, v65
	v_rcp_f32_e32 v64, v64
	v_max_f32_e32 v65, v92, v92
	v_add_u32_e32 v68, s13, v86
	v_mul_f32_e32 v64, v69, v64
	v_cvt_pk_bf16_f32 v64, v64, s0
	ds_write_b16 v80, v64 offset:21648
	v_fma_f32 v64, v66, v84, v88
	v_max_f32_e64 v64, |v64|, v65
	v_rcp_f32_e32 v64, v64
	s_nop 0
	v_mul_f32_e32 v64, v70, v64
	v_cvt_pk_bf16_f32 v64, v64, s0
	ds_write_b16 v80, v64 offset:22176
	v_max_f32_e32 v64, v93, v93
	v_max_f32_e64 v64, |v89|, v64
	v_rcp_f32_e32 v64, v64
	s_nop 0
	v_mul_f32_e32 v64, v71, v64
	v_cvt_pk_bf16_f32 v64, v64, s0
	ds_write_b16 v80, v64 offset:22704
	v_add_u32_e32 v64, s12, v86
	v_add_u32_e32 v86, s42, v86
	ds_read_b128 v[64:67], v64
	ds_read_b128 v[68:71], v68
	ds_read_b128 v[82:85], v82
	ds_read_b128 v[86:89], v86
	s_waitcnt lgkmcnt(1)
	v_fma_f32 v64, v64, v68, v82
	s_waitcnt lgkmcnt(0)
	v_max_f32_e32 v68, v86, v86
	v_max_f32_e64 v64, |v64|, v68
	v_rcp_f32_e32 v64, v64
	v_fmac_f32_e32 v85, v67, v71
	v_or_b32_e32 v82, 0xe0, v217
	v_add_u32_e32 v68, s13, v82
	v_mul_f32_e32 v64, v72, v64
	v_cvt_pk_bf16_f32 v64, v64, s0
	ds_write_b16 v81, v64 offset:21120
	v_fma_f32 v64, v65, v69, v83
	v_max_f32_e32 v65, v87, v87
	v_max_f32_e64 v64, |v64|, v65
	v_rcp_f32_e32 v64, v64
	v_max_f32_e32 v65, v88, v88
	v_add_u32_e32 v72, s15, v82
	v_mul_f32_e32 v64, v73, v64
	v_cvt_pk_bf16_f32 v64, v64, s0
	ds_write_b16 v80, v64 offset:25872
	v_fma_f32 v64, v66, v70, v84
	v_max_f32_e64 v64, |v64|, v65
	v_rcp_f32_e32 v64, v64
	s_nop 0
	v_mul_f32_e32 v64, v74, v64
	v_cvt_pk_bf16_f32 v64, v64, s0
	ds_write_b16 v80, v64 offset:26400
	v_max_f32_e32 v64, v89, v89
	v_max_f32_e64 v64, |v85|, v64
	v_rcp_f32_e32 v64, v64
	s_nop 0
	v_mul_f32_e32 v64, v75, v64
	v_cvt_pk_bf16_f32 v64, v64, s0
	ds_write_b16 v80, v64 offset:26928
	v_add_u32_e32 v64, s12, v82
	v_add_u32_e32 v82, s42, v82
	ds_read_b128 v[64:67], v64
	ds_read_b128 v[68:71], v68
	ds_read_b128 v[72:75], v72
	ds_read_b128 v[82:85], v82
	s_waitcnt lgkmcnt(1)
	v_fma_f32 v64, v64, v68, v72
	s_waitcnt lgkmcnt(0)
	v_max_f32_e32 v68, v82, v82
	v_max_f32_e64 v64, |v64|, v68
	v_rcp_f32_e32 v64, v64
	v_fmac_f32_e32 v75, v67, v71
	v_mad_u32_u24 v72, v215, s93, v208
	v_mul_f32_e32 v64, v76, v64
	v_cvt_pk_bf16_f32 v64, v64, s0
	ds_write_b16 v81, v64 offset:25344
	v_fma_f32 v64, v65, v69, v73
	v_max_f32_e32 v65, v83, v83
	v_max_f32_e64 v64, |v64|, v65
	v_rcp_f32_e32 v64, v64
	v_max_f32_e32 v65, v84, v84
	v_mad_u32_u24 v73, v216, s93, v208
	v_mul_f32_e32 v64, v77, v64
	v_cvt_pk_bf16_f32 v64, v64, s0
	ds_write_b16 v80, v64 offset:30096
	v_fma_f32 v64, v66, v70, v74
	v_max_f32_e64 v64, |v64|, v65
	v_rcp_f32_e32 v64, v64
	v_and_b32_e32 v74, 3, v214
	v_cmp_eq_u32_e32 vcc, 0, v74
	v_mul_f32_e32 v64, v78, v64
	v_cvt_pk_bf16_f32 v64, v64, s0
	ds_write_b16 v80, v64 offset:30624
	v_max_f32_e32 v64, v85, v85
	v_max_f32_e64 v64, |v75|, v64
	v_rcp_f32_e32 v64, v64
	s_nop 0
	v_mul_f32_e32 v64, v79, v64
	v_cvt_pk_bf16_f32 v64, v64, s0
	ds_write_b16 v80, v64 offset:31152
	ds_read_b128 v[64:67], v72 offset:34816
	ds_read_b128 v[68:71], v72 offset:34848
	ds_read_b128 v[76:79], v72 offset:34880
	ds_read_b128 v[80:83], v72 offset:34912
	ds_read_b128 v[84:87], v73 offset:34816
	ds_read_b128 v[88:91], v73 offset:34848
	s_waitcnt lgkmcnt(5)
	v_mfma_f32_32x32x16_bf16 v[0:15], v[64:67], v[168:171], v[0:15]
	ds_read_b128 v[64:67], v73 offset:34880
	s_waitcnt lgkmcnt(5)
	v_mfma_f32_32x32x16_bf16 v[0:15], v[68:71], v[164:167], v[0:15]
	ds_read_b128 v[68:71], v73 offset:34912
	s_waitcnt lgkmcnt(5)
	v_mfma_f32_32x32x16_bf16 v[0:15], v[76:79], v[160:163], v[0:15]
	ds_read_b128 v[76:79], v72 offset:44032
	s_waitcnt lgkmcnt(5)
	v_mfma_f32_32x32x16_bf16 v[0:15], v[80:83], v[156:159], v[0:15]
	ds_read_b128 v[80:83], v72 offset:44064
	s_waitcnt lgkmcnt(5)
	v_mfma_f32_32x32x16_bf16 v[16:31], v[84:87], v[168:171], v[16:31]
	ds_read_b128 v[84:87], v72 offset:44096
	s_waitcnt lgkmcnt(5)
	v_mfma_f32_32x32x16_bf16 v[16:31], v[88:91], v[164:167], v[16:31]
	ds_read_b128 v[88:91], v72 offset:44128
	s_waitcnt lgkmcnt(5)
	v_mfma_f32_32x32x16_bf16 v[16:31], v[64:67], v[160:163], v[16:31]
	ds_read_b128 v[64:67], v72 offset:48640
	s_waitcnt lgkmcnt(5)
	v_mfma_f32_32x32x16_bf16 v[16:31], v[68:71], v[156:159], v[16:31]
	ds_read_b128 v[68:71], v72 offset:48672
	s_waitcnt lgkmcnt(5)
	v_mfma_f32_32x32x16_bf16 v[32:47], v[76:79], v[168:171], v[32:47]
	ds_read_b128 v[76:79], v72 offset:48704
	s_waitcnt lgkmcnt(5)
	v_mfma_f32_32x32x16_bf16 v[32:47], v[80:83], v[164:167], v[32:47]
	ds_read_b128 v[80:83], v72 offset:48736
	s_waitcnt lgkmcnt(5)
	v_mfma_f32_32x32x16_bf16 v[32:47], v[84:87], v[160:163], v[32:47]
	s_waitcnt lgkmcnt(4)
	v_mfma_f32_32x32x16_bf16 v[32:47], v[88:91], v[156:159], v[32:47]
	s_waitcnt lgkmcnt(3)
	v_mfma_f32_32x32x16_bf16 v[48:63], v[64:67], v[168:171], v[48:63]
	s_waitcnt lgkmcnt(2)
	v_mfma_f32_32x32x16_bf16 v[48:63], v[68:71], v[164:167], v[48:63]
	s_waitcnt lgkmcnt(1)
	v_mfma_f32_32x32x16_bf16 v[48:63], v[76:79], v[160:163], v[48:63]
	s_waitcnt lgkmcnt(0)
	v_mfma_f32_32x32x16_bf16 v[48:63], v[80:83], v[156:159], v[48:63]
	v_ashrrev_i32_e32 v64, 2, v214
	v_mul_lo_u32 v65, v64, s93
	v_lshlrev_b32_e32 v66, 5, v74
	v_add3_u32 v65, 0, v65, v66
	ds_read_b128 v[66:69], v65 offset:34816
	ds_read_b128 v[70:73], v65 offset:34832
	s_waitcnt lgkmcnt(1)
	v_lshlrev_b32_e32 v65, 16, v66
	v_and_b32_e32 v66, 0xffff0000, v66
	v_add_f32_e32 v65, v65, v66
	s_waitcnt lgkmcnt(0)
	v_lshlrev_b32_e32 v66, 16, v70
	v_and_b32_e32 v70, 0xffff0000, v70
	v_add_f32_e32 v66, v66, v70
	v_add_f32_e32 v65, v65, v66
	v_lshlrev_b32_e32 v66, 16, v67
	v_and_b32_e32 v67, 0xffff0000, v67
	v_add_f32_e32 v66, v66, v67
	v_lshlrev_b32_e32 v67, 16, v71
	v_and_b32_e32 v70, 0xffff0000, v71
	v_add_f32_e32 v67, v67, v70
	v_add_f32_e32 v65, 0, v65
	v_add_f32_e32 v66, v66, v67
	v_add_f32_e32 v65, v66, v65
	v_lshlrev_b32_e32 v66, 16, v68
	v_and_b32_e32 v67, 0xffff0000, v68
	v_add_f32_e32 v66, v66, v67
	v_lshlrev_b32_e32 v67, 16, v72
	v_and_b32_e32 v68, 0xffff0000, v72
	v_add_f32_e32 v67, v67, v68
	v_add_f32_e32 v66, v66, v67
	v_add_f32_e32 v65, v66, v65
	v_lshlrev_b32_e32 v66, 16, v69
	v_and_b32_e32 v67, 0xffff0000, v69
	v_add_f32_e32 v66, v66, v67
	v_lshlrev_b32_e32 v67, 16, v73
	v_and_b32_e32 v68, 0xffff0000, v73
	v_add_f32_e32 v67, v67, v68
	v_add_f32_e32 v66, v66, v67
	v_add_f32_e32 v65, v66, v65
	ds_bpermute_b32 v66, v189, v65
	s_waitcnt lgkmcnt(0)
	v_add_f32_e32 v65, v65, v66
	ds_bpermute_b32 v66, v191, v65
	s_and_saveexec_b64 s[12:13], vcc
	s_cbranch_execz .LBB0_206
	v_lshl_add_u32 v64, v64, 2, 0
	v_add_u32_e32 v64, 0x21000, v64
	s_waitcnt lgkmcnt(0)
	v_add_f32_e32 v65, v65, v66
	ds_read_b32 v66, v64
	s_waitcnt lgkmcnt(0)
	v_fmac_f32_e32 v65, v96, v66
	ds_write_b32 v64, v65
	s_branch .LBB0_206

.LBB0_479:
	v_readlane_b32 s3, v254, 60
	s_and_b32 s3, s3, 0xffff
	s_cmp_lg_u32 s3, 6
	s_cbranch_scc1 .Lkn_skip
	v_readlane_b32 s4, v254, 48
	s_cmpk_lt_u32 s4, 32
	s_cbranch_scc1 .Lkn_skip
	v_lshrrev_b32_e32 v0, 6, v222
	v_and_b32_e32 v1, 63, v222
	v_readlane_b32 s5, v250, 0
	v_readfirstlane_b32 s3, v0
	v_readlane_b32 s82, v250, 2
	v_readlane_b32 s83, v250, 3
	s_sub_u32 s4, s4, 32
	s_lshl_b32 s4, s4, 3
	s_add_i32 s4, s4, s3
	s_sub_u32 s5, s5, 32
	s_lshl_b32 s5, s5, 13
	s_load_dwordx2 s[18:19], s[82:83], 0x70
	s_add_u32 s12, s74, 0x17000000
	s_addc_u32 s13, s75, 0
	s_and_b32 s13, s13, 0xffff
	s_mov_b32 s14, 0x4000000
	s_mov_b32 s15, 0x20000
	s_lshl_b32 s11, s4, 10
	v_lshlrev_b32_e32 v88, 4, v1
	s_and_b32 s16, s4, 1
	s_lshl_b32 s16, s16, 11
	v_lshl_add_u32 v89, v1, 5, s16
	s_waitcnt lgkmcnt(0)
	global_load_dwordx4 v[32:35], v89, s[18:19]
	global_load_dwordx4 v[36:39], v89, s[18:19] offset:16
	s_mov_b32 s20, s11
	buffer_load_dwordx4 v[0:3], v88, s[12:15], s11 offen sc1
	s_add_u32 s11, s11, s5
	buffer_load_dwordx4 v[4:7], v88, s[12:15], s11 offen sc1
	s_add_u32 s11, s11, s5
	buffer_load_dwordx4 v[8:11], v88, s[12:15], s11 offen sc1
	s_add_u32 s11, s11, s5
	buffer_load_dwordx4 v[12:15], v88, s[12:15], s11 offen sc1
	s_add_u32 s11, s11, s5
.Lkn_loop:
	buffer_load_dwordx4 v[16:19], v88, s[12:15], s11 offen sc1
	s_add_u32 s11, s11, s5
	buffer_load_dwordx4 v[20:23], v88, s[12:15], s11 offen sc1
	s_add_u32 s11, s11, s5
	buffer_load_dwordx4 v[24:27], v88, s[12:15], s11 offen sc1
	s_add_u32 s11, s11, s5
	buffer_load_dwordx4 v[28:31], v88, s[12:15], s11 offen sc1
	s_add_u32 s11, s11, s5
	s_waitcnt vmcnt(4)
	v_lshlrev_b32_e32 v40, 16, v0
	v_and_b32_e32 v41, 0xffff0000, v0
	v_lshlrev_b32_e32 v42, 16, v1
	v_and_b32_e32 v43, 0xffff0000, v1
	v_lshlrev_b32_e32 v44, 16, v2
	v_and_b32_e32 v45, 0xffff0000, v2
	v_lshlrev_b32_e32 v46, 16, v3
	v_and_b32_e32 v47, 0xffff0000, v3
	v_mul_f32_e32 v48, v41, v41
	v_mul_f32_e32 v49, v43, v43
	v_mul_f32_e32 v50, v45, v45
	v_mul_f32_e32 v51, v47, v47
	v_fma_f32 v48, v40, v40, v48
	v_fma_f32 v49, v42, v42, v49
	v_fma_f32 v50, v44, v44, v50
	v_fma_f32 v51, v46, v46, v51
	v_add_f32_e32 v52, v48, v49
	v_add_f32_e32 v52, v52, v50
	v_add_f32_e32 v52, v52, v51
	s_nop 1
	v_add_f32_dpp v52, v52, v52 quad_perm:[1,0,3,2] row_mask:0xf bank_mask:0xf
	s_nop 1
	v_add_f32_dpp v52, v52, v52 quad_perm:[2,3,0,1] row_mask:0xf bank_mask:0xf
	s_nop 1
	v_add_f32_dpp v52, v52, v52 row_half_mirror row_mask:0xf bank_mask:0xf
	v_fmamk_f32 v53, v52, 0x3c800000, v225
	v_mul_f32_e32 v54, 0x4b800000, v53
	v_cmp_gt_f32_e32 vcc, 0x800000, v53
	s_nop 1
	v_cndmask_b32_e32 v53, v53, v54, vcc
	v_rsq_f32_e32 v53, v53
	s_nop 0
	v_mul_f32_e32 v54, 0x45800000, v53
	v_cndmask_b32_e32 v56, v53, v54, vcc
	v_pk_mul_f32 v[58:59], v[32:33], v[56:57] op_sel_hi:[1,0]
	v_pk_mul_f32 v[60:61], v[34:35], v[56:57] op_sel_hi:[1,0]
	v_pk_mul_f32 v[62:63], v[36:37], v[56:57] op_sel_hi:[1,0]
	v_pk_mul_f32 v[64:65], v[38:39], v[56:57] op_sel_hi:[1,0]
	v_pk_mul_f32 v[40:41], v[58:59], v[40:41]
	v_pk_mul_f32 v[42:43], v[60:61], v[42:43]
	v_pk_mul_f32 v[44:45], v[62:63], v[44:45]
	v_pk_mul_f32 v[46:47], v[64:65], v[46:47]
	v_cvt_pk_bf16_f32 v72, v40, v41
	v_cvt_pk_bf16_f32 v73, v42, v43
	v_cvt_pk_bf16_f32 v74, v44, v45
	v_cvt_pk_bf16_f32 v75, v46, v47
	buffer_store_dwordx4 v[72:75], v88, s[12:15], s20 offen sc1
	s_add_u32 s20, s20, s5
	v_lshlrev_b32_e32 v40, 16, v4
	v_and_b32_e32 v41, 0xffff0000, v4
	v_lshlrev_b32_e32 v42, 16, v5
	v_and_b32_e32 v43, 0xffff0000, v5
	v_lshlrev_b32_e32 v44, 16, v6
	v_and_b32_e32 v45, 0xffff0000, v6
	v_lshlrev_b32_e32 v46, 16, v7
	v_and_b32_e32 v47, 0xffff0000, v7
	v_mul_f32_e32 v48, v41, v41
	v_mul_f32_e32 v49, v43, v43
	v_mul_f32_e32 v50, v45, v45
	v_mul_f32_e32 v51, v47, v47
	v_fma_f32 v48, v40, v40, v48
	v_fma_f32 v49, v42, v42, v49
	v_fma_f32 v50, v44, v44, v50
	v_fma_f32 v51, v46, v46, v51
	v_add_f32_e32 v52, v48, v49
	v_add_f32_e32 v52, v52, v50
	v_add_f32_e32 v52, v52, v51
	s_nop 1
	v_add_f32_dpp v52, v52, v52 quad_perm:[1,0,3,2] row_mask:0xf bank_mask:0xf
	s_nop 1
	v_add_f32_dpp v52, v52, v52 quad_perm:[2,3,0,1] row_mask:0xf bank_mask:0xf
	s_nop 1
	v_add_f32_dpp v52, v52, v52 row_half_mirror row_mask:0xf bank_mask:0xf
	v_fmamk_f32 v53, v52, 0x3c800000, v225
	v_mul_f32_e32 v54, 0x4b800000, v53
	v_cmp_gt_f32_e32 vcc, 0x800000, v53
	s_nop 1
	v_cndmask_b32_e32 v53, v53, v54, vcc
	v_rsq_f32_e32 v53, v53
	s_nop 0
	v_mul_f32_e32 v54, 0x45800000, v53
	v_cndmask_b32_e32 v56, v53, v54, vcc
	v_pk_mul_f32 v[58:59], v[32:33], v[56:57] op_sel_hi:[1,0]
	v_pk_mul_f32 v[60:61], v[34:35], v[56:57] op_sel_hi:[1,0]
	v_pk_mul_f32 v[62:63], v[36:37], v[56:57] op_sel_hi:[1,0]
	v_pk_mul_f32 v[64:65], v[38:39], v[56:57] op_sel_hi:[1,0]
	v_pk_mul_f32 v[40:41], v[58:59], v[40:41]
	v_pk_mul_f32 v[42:43], v[60:61], v[42:43]
	v_pk_mul_f32 v[44:45], v[62:63], v[44:45]
	v_pk_mul_f32 v[46:47], v[64:65], v[46:47]
	v_cvt_pk_bf16_f32 v76, v40, v41
	v_cvt_pk_bf16_f32 v77, v42, v43
	v_cvt_pk_bf16_f32 v78, v44, v45
	v_cvt_pk_bf16_f32 v79, v46, v47
	buffer_store_dwordx4 v[76:79], v88, s[12:15], s20 offen sc1
	s_add_u32 s20, s20, s5
	v_lshlrev_b32_e32 v40, 16, v8
	v_and_b32_e32 v41, 0xffff0000, v8
	v_lshlrev_b32_e32 v42, 16, v9
	v_and_b32_e32 v43, 0xffff0000, v9
	v_lshlrev_b32_e32 v44, 16, v10
	v_and_b32_e32 v45, 0xffff0000, v10
	v_lshlrev_b32_e32 v46, 16, v11
	v_and_b32_e32 v47, 0xffff0000, v11
	v_mul_f32_e32 v48, v41, v41
	v_mul_f32_e32 v49, v43, v43
	v_mul_f32_e32 v50, v45, v45
	v_mul_f32_e32 v51, v47, v47
	v_fma_f32 v48, v40, v40, v48
	v_fma_f32 v49, v42, v42, v49
	v_fma_f32 v50, v44, v44, v50
	v_fma_f32 v51, v46, v46, v51
	v_add_f32_e32 v52, v48, v49
	v_add_f32_e32 v52, v52, v50
	v_add_f32_e32 v52, v52, v51
	s_nop 1
	v_add_f32_dpp v52, v52, v52 quad_perm:[1,0,3,2] row_mask:0xf bank_mask:0xf
	s_nop 1
	v_add_f32_dpp v52, v52, v52 quad_perm:[2,3,0,1] row_mask:0xf bank_mask:0xf
	s_nop 1
	v_add_f32_dpp v52, v52, v52 row_half_mirror row_mask:0xf bank_mask:0xf
	v_fmamk_f32 v53, v52, 0x3c800000, v225
	v_mul_f32_e32 v54, 0x4b800000, v53
	v_cmp_gt_f32_e32 vcc, 0x800000, v53
	s_nop 1
	v_cndmask_b32_e32 v53, v53, v54, vcc
	v_rsq_f32_e32 v53, v53
	s_nop 0
	v_mul_f32_e32 v54, 0x45800000, v53
	v_cndmask_b32_e32 v56, v53, v54, vcc
	v_pk_mul_f32 v[58:59], v[32:33], v[56:57] op_sel_hi:[1,0]
	v_pk_mul_f32 v[60:61], v[34:35], v[56:57] op_sel_hi:[1,0]
	v_pk_mul_f32 v[62:63], v[36:37], v[56:57] op_sel_hi:[1,0]
	v_pk_mul_f32 v[64:65], v[38:39], v[56:57] op_sel_hi:[1,0]
	v_pk_mul_f32 v[40:41], v[58:59], v[40:41]
	v_pk_mul_f32 v[42:43], v[60:61], v[42:43]
	v_pk_mul_f32 v[44:45], v[62:63], v[44:45]
	v_pk_mul_f32 v[46:47], v[64:65], v[46:47]
	v_cvt_pk_bf16_f32 v80, v40, v41
	v_cvt_pk_bf16_f32 v81, v42, v43
	v_cvt_pk_bf16_f32 v82, v44, v45
	v_cvt_pk_bf16_f32 v83, v46, v47
	buffer_store_dwordx4 v[80:83], v88, s[12:15], s20 offen sc1
	s_add_u32 s20, s20, s5
	v_lshlrev_b32_e32 v40, 16, v12
	v_and_b32_e32 v41, 0xffff0000, v12
	v_lshlrev_b32_e32 v42, 16, v13
	v_and_b32_e32 v43, 0xffff0000, v13
	v_lshlrev_b32_e32 v44, 16, v14
	v_and_b32_e32 v45, 0xffff0000, v14
	v_lshlrev_b32_e32 v46, 16, v15
	v_and_b32_e32 v47, 0xffff0000, v15
	v_mul_f32_e32 v48, v41, v41
	v_mul_f32_e32 v49, v43, v43
	v_mul_f32_e32 v50, v45, v45
	v_mul_f32_e32 v51, v47, v47
	v_fma_f32 v48, v40, v40, v48
	v_fma_f32 v49, v42, v42, v49
	v_fma_f32 v50, v44, v44, v50
	v_fma_f32 v51, v46, v46, v51
	v_add_f32_e32 v52, v48, v49
	v_add_f32_e32 v52, v52, v50
	v_add_f32_e32 v52, v52, v51
	s_nop 1
	v_add_f32_dpp v52, v52, v52 quad_perm:[1,0,3,2] row_mask:0xf bank_mask:0xf
	s_nop 1
	v_add_f32_dpp v52, v52, v52 quad_perm:[2,3,0,1] row_mask:0xf bank_mask:0xf
	s_nop 1
	v_add_f32_dpp v52, v52, v52 row_half_mirror row_mask:0xf bank_mask:0xf
	v_fmamk_f32 v53, v52, 0x3c800000, v225
	v_mul_f32_e32 v54, 0x4b800000, v53
	v_cmp_gt_f32_e32 vcc, 0x800000, v53
	s_nop 1
	v_cndmask_b32_e32 v53, v53, v54, vcc
	v_rsq_f32_e32 v53, v53
	s_nop 0
	v_mul_f32_e32 v54, 0x45800000, v53
	v_cndmask_b32_e32 v56, v53, v54, vcc
	v_pk_mul_f32 v[58:59], v[32:33], v[56:57] op_sel_hi:[1,0]
	v_pk_mul_f32 v[60:61], v[34:35], v[56:57] op_sel_hi:[1,0]
	v_pk_mul_f32 v[62:63], v[36:37], v[56:57] op_sel_hi:[1,0]
	v_pk_mul_f32 v[64:65], v[38:39], v[56:57] op_sel_hi:[1,0]
	v_pk_mul_f32 v[40:41], v[58:59], v[40:41]
	v_pk_mul_f32 v[42:43], v[60:61], v[42:43]
	v_pk_mul_f32 v[44:45], v[62:63], v[44:45]
	v_pk_mul_f32 v[46:47], v[64:65], v[46:47]
	v_cvt_pk_bf16_f32 v84, v40, v41
	v_cvt_pk_bf16_f32 v85, v42, v43
	v_cvt_pk_bf16_f32 v86, v44, v45
	v_cvt_pk_bf16_f32 v87, v46, v47
	buffer_store_dwordx4 v[84:87], v88, s[12:15], s20 offen sc1
	s_add_u32 s20, s20, s5
	buffer_load_dwordx4 v[0:3], v88, s[12:15], s11 offen sc1
	s_add_u32 s11, s11, s5
	buffer_load_dwordx4 v[4:7], v88, s[12:15], s11 offen sc1
	s_add_u32 s11, s11, s5
	buffer_load_dwordx4 v[8:11], v88, s[12:15], s11 offen sc1
	s_add_u32 s11, s11, s5
	buffer_load_dwordx4 v[12:15], v88, s[12:15], s11 offen sc1
	s_add_u32 s11, s11, s5
	s_waitcnt vmcnt(8)
	v_lshlrev_b32_e32 v40, 16, v16
	v_and_b32_e32 v41, 0xffff0000, v16
	v_lshlrev_b32_e32 v42, 16, v17
	v_and_b32_e32 v43, 0xffff0000, v17
	v_lshlrev_b32_e32 v44, 16, v18
	v_and_b32_e32 v45, 0xffff0000, v18
	v_lshlrev_b32_e32 v46, 16, v19
	v_and_b32_e32 v47, 0xffff0000, v19
	v_mul_f32_e32 v48, v41, v41
	v_mul_f32_e32 v49, v43, v43
	v_mul_f32_e32 v50, v45, v45
	v_mul_f32_e32 v51, v47, v47
	v_fma_f32 v48, v40, v40, v48
	v_fma_f32 v49, v42, v42, v49
	v_fma_f32 v50, v44, v44, v50
	v_fma_f32 v51, v46, v46, v51
	v_add_f32_e32 v52, v48, v49
	v_add_f32_e32 v52, v52, v50
	v_add_f32_e32 v52, v52, v51
	s_nop 1
	v_add_f32_dpp v52, v52, v52 quad_perm:[1,0,3,2] row_mask:0xf bank_mask:0xf
	s_nop 1
	v_add_f32_dpp v52, v52, v52 quad_perm:[2,3,0,1] row_mask:0xf bank_mask:0xf
	s_nop 1
	v_add_f32_dpp v52, v52, v52 row_half_mirror row_mask:0xf bank_mask:0xf
	v_fmamk_f32 v53, v52, 0x3c800000, v225
	v_mul_f32_e32 v54, 0x4b800000, v53
	v_cmp_gt_f32_e32 vcc, 0x800000, v53
	s_nop 1
	v_cndmask_b32_e32 v53, v53, v54, vcc
	v_rsq_f32_e32 v53, v53
	s_nop 0
	v_mul_f32_e32 v54, 0x45800000, v53
	v_cndmask_b32_e32 v56, v53, v54, vcc
	v_pk_mul_f32 v[58:59], v[32:33], v[56:57] op_sel_hi:[1,0]
	v_pk_mul_f32 v[60:61], v[34:35], v[56:57] op_sel_hi:[1,0]
	v_pk_mul_f32 v[62:63], v[36:37], v[56:57] op_sel_hi:[1,0]
	v_pk_mul_f32 v[64:65], v[38:39], v[56:57] op_sel_hi:[1,0]
	v_pk_mul_f32 v[40:41], v[58:59], v[40:41]
	v_pk_mul_f32 v[42:43], v[60:61], v[42:43]
	v_pk_mul_f32 v[44:45], v[62:63], v[44:45]
	v_pk_mul_f32 v[46:47], v[64:65], v[46:47]
	v_cvt_pk_bf16_f32 v72, v40, v41
	v_cvt_pk_bf16_f32 v73, v42, v43
	v_cvt_pk_bf16_f32 v74, v44, v45
	v_cvt_pk_bf16_f32 v75, v46, v47
	buffer_store_dwordx4 v[72:75], v88, s[12:15], s20 offen sc1
	s_add_u32 s20, s20, s5
	v_lshlrev_b32_e32 v40, 16, v20
	v_and_b32_e32 v41, 0xffff0000, v20
	v_lshlrev_b32_e32 v42, 16, v21
	v_and_b32_e32 v43, 0xffff0000, v21
	v_lshlrev_b32_e32 v44, 16, v22
	v_and_b32_e32 v45, 0xffff0000, v22
	v_lshlrev_b32_e32 v46, 16, v23
	v_and_b32_e32 v47, 0xffff0000, v23
	v_mul_f32_e32 v48, v41, v41
	v_mul_f32_e32 v49, v43, v43
	v_mul_f32_e32 v50, v45, v45
	v_mul_f32_e32 v51, v47, v47
	v_fma_f32 v48, v40, v40, v48
	v_fma_f32 v49, v42, v42, v49
	v_fma_f32 v50, v44, v44, v50
	v_fma_f32 v51, v46, v46, v51
	v_add_f32_e32 v52, v48, v49
	v_add_f32_e32 v52, v52, v50
	v_add_f32_e32 v52, v52, v51
	s_nop 1
	v_add_f32_dpp v52, v52, v52 quad_perm:[1,0,3,2] row_mask:0xf bank_mask:0xf
	s_nop 1
	v_add_f32_dpp v52, v52, v52 quad_perm:[2,3,0,1] row_mask:0xf bank_mask:0xf
	s_nop 1
	v_add_f32_dpp v52, v52, v52 row_half_mirror row_mask:0xf bank_mask:0xf
	v_fmamk_f32 v53, v52, 0x3c800000, v225
	v_mul_f32_e32 v54, 0x4b800000, v53
	v_cmp_gt_f32_e32 vcc, 0x800000, v53
	s_nop 1
	v_cndmask_b32_e32 v53, v53, v54, vcc
	v_rsq_f32_e32 v53, v53
	s_nop 0
	v_mul_f32_e32 v54, 0x45800000, v53
	v_cndmask_b32_e32 v56, v53, v54, vcc
	v_pk_mul_f32 v[58:59], v[32:33], v[56:57] op_sel_hi:[1,0]
	v_pk_mul_f32 v[60:61], v[34:35], v[56:57] op_sel_hi:[1,0]
	v_pk_mul_f32 v[62:63], v[36:37], v[56:57] op_sel_hi:[1,0]
	v_pk_mul_f32 v[64:65], v[38:39], v[56:57] op_sel_hi:[1,0]
	v_pk_mul_f32 v[40:41], v[58:59], v[40:41]
	v_pk_mul_f32 v[42:43], v[60:61], v[42:43]
	v_pk_mul_f32 v[44:45], v[62:63], v[44:45]
	v_pk_mul_f32 v[46:47], v[64:65], v[46:47]
	v_cvt_pk_bf16_f32 v76, v40, v41
	v_cvt_pk_bf16_f32 v77, v42, v43
	v_cvt_pk_bf16_f32 v78, v44, v45
	v_cvt_pk_bf16_f32 v79, v46, v47
	buffer_store_dwordx4 v[76:79], v88, s[12:15], s20 offen sc1
	s_add_u32 s20, s20, s5
	v_lshlrev_b32_e32 v40, 16, v24
	v_and_b32_e32 v41, 0xffff0000, v24
	v_lshlrev_b32_e32 v42, 16, v25
	v_and_b32_e32 v43, 0xffff0000, v25
	v_lshlrev_b32_e32 v44, 16, v26
	v_and_b32_e32 v45, 0xffff0000, v26
	v_lshlrev_b32_e32 v46, 16, v27
	v_and_b32_e32 v47, 0xffff0000, v27
	v_mul_f32_e32 v48, v41, v41
	v_mul_f32_e32 v49, v43, v43
	v_mul_f32_e32 v50, v45, v45
	v_mul_f32_e32 v51, v47, v47
	v_fma_f32 v48, v40, v40, v48
	v_fma_f32 v49, v42, v42, v49
	v_fma_f32 v50, v44, v44, v50
	v_fma_f32 v51, v46, v46, v51
	v_add_f32_e32 v52, v48, v49
	v_add_f32_e32 v52, v52, v50
	v_add_f32_e32 v52, v52, v51
	s_nop 1
	v_add_f32_dpp v52, v52, v52 quad_perm:[1,0,3,2] row_mask:0xf bank_mask:0xf
	s_nop 1
	v_add_f32_dpp v52, v52, v52 quad_perm:[2,3,0,1] row_mask:0xf bank_mask:0xf
	s_nop 1
	v_add_f32_dpp v52, v52, v52 row_half_mirror row_mask:0xf bank_mask:0xf
	v_fmamk_f32 v53, v52, 0x3c800000, v225
	v_mul_f32_e32 v54, 0x4b800000, v53
	v_cmp_gt_f32_e32 vcc, 0x800000, v53
	s_nop 1
	v_cndmask_b32_e32 v53, v53, v54, vcc
	v_rsq_f32_e32 v53, v53
	s_nop 0
	v_mul_f32_e32 v54, 0x45800000, v53
	v_cndmask_b32_e32 v56, v53, v54, vcc
	v_pk_mul_f32 v[58:59], v[32:33], v[56:57] op_sel_hi:[1,0]
	v_pk_mul_f32 v[60:61], v[34:35], v[56:57] op_sel_hi:[1,0]
	v_pk_mul_f32 v[62:63], v[36:37], v[56:57] op_sel_hi:[1,0]
	v_pk_mul_f32 v[64:65], v[38:39], v[56:57] op_sel_hi:[1,0]
	v_pk_mul_f32 v[40:41], v[58:59], v[40:41]
	v_pk_mul_f32 v[42:43], v[60:61], v[42:43]
	v_pk_mul_f32 v[44:45], v[62:63], v[44:45]
	v_pk_mul_f32 v[46:47], v[64:65], v[46:47]
	v_cvt_pk_bf16_f32 v80, v40, v41
	v_cvt_pk_bf16_f32 v81, v42, v43
	v_cvt_pk_bf16_f32 v82, v44, v45
	v_cvt_pk_bf16_f32 v83, v46, v47
	buffer_store_dwordx4 v[80:83], v88, s[12:15], s20 offen sc1
	s_add_u32 s20, s20, s5
	v_lshlrev_b32_e32 v40, 16, v28
	v_and_b32_e32 v41, 0xffff0000, v28
	v_lshlrev_b32_e32 v42, 16, v29
	v_and_b32_e32 v43, 0xffff0000, v29
	v_lshlrev_b32_e32 v44, 16, v30
	v_and_b32_e32 v45, 0xffff0000, v30
	v_lshlrev_b32_e32 v46, 16, v31
	v_and_b32_e32 v47, 0xffff0000, v31
	v_mul_f32_e32 v48, v41, v41
	v_mul_f32_e32 v49, v43, v43
	v_mul_f32_e32 v50, v45, v45
	v_mul_f32_e32 v51, v47, v47
	v_fma_f32 v48, v40, v40, v48
	v_fma_f32 v49, v42, v42, v49
	v_fma_f32 v50, v44, v44, v50
	v_fma_f32 v51, v46, v46, v51
	v_add_f32_e32 v52, v48, v49
	v_add_f32_e32 v52, v52, v50
	v_add_f32_e32 v52, v52, v51
	s_nop 1
	v_add_f32_dpp v52, v52, v52 quad_perm:[1,0,3,2] row_mask:0xf bank_mask:0xf
	s_nop 1
	v_add_f32_dpp v52, v52, v52 quad_perm:[2,3,0,1] row_mask:0xf bank_mask:0xf
	s_nop 1
	v_add_f32_dpp v52, v52, v52 row_half_mirror row_mask:0xf bank_mask:0xf
	v_fmamk_f32 v53, v52, 0x3c800000, v225
	v_mul_f32_e32 v54, 0x4b800000, v53
	v_cmp_gt_f32_e32 vcc, 0x800000, v53
	s_nop 1
	v_cndmask_b32_e32 v53, v53, v54, vcc
	v_rsq_f32_e32 v53, v53
	s_nop 0
	v_mul_f32_e32 v54, 0x45800000, v53
	v_cndmask_b32_e32 v56, v53, v54, vcc
	v_pk_mul_f32 v[58:59], v[32:33], v[56:57] op_sel_hi:[1,0]
	v_pk_mul_f32 v[60:61], v[34:35], v[56:57] op_sel_hi:[1,0]
	v_pk_mul_f32 v[62:63], v[36:37], v[56:57] op_sel_hi:[1,0]
	v_pk_mul_f32 v[64:65], v[38:39], v[56:57] op_sel_hi:[1,0]
	v_pk_mul_f32 v[40:41], v[58:59], v[40:41]
	v_pk_mul_f32 v[42:43], v[60:61], v[42:43]
	v_pk_mul_f32 v[44:45], v[62:63], v[44:45]
	v_pk_mul_f32 v[46:47], v[64:65], v[46:47]
	v_cvt_pk_bf16_f32 v84, v40, v41
	v_cvt_pk_bf16_f32 v85, v42, v43
	v_cvt_pk_bf16_f32 v86, v44, v45
	v_cvt_pk_bf16_f32 v87, v46, v47
	buffer_store_dwordx4 v[84:87], v88, s[12:15], s20 offen sc1
	s_add_u32 s20, s20, s5
	s_cmp_lt_u32 s20, 0x4000000
	s_cbranch_scc1 .Lkn_loop
	s_waitcnt vmcnt(0)
